# v33 + wait-state pads (VALU-written SGPR/VCC read by VALU) in the panel/group barrier code
# speedup vs baseline: 1.0150x; 1.0023x over previous
; __device__ __forceinline__ unsigned xb_ld(unsigned* p)              { return __hip_atomic_load(p, __ATOMIC_RELAXED, __HIP_MEMORY_SCOPE_AGENT); }
; __device__ __forceinline__ unsigned xb_add(unsigned* p, unsigned v) { return __hip_atomic_fetch_add(p, v, __ATOMIC_RELAXED, __HIP_MEMORY_SCOPE_AGENT); }
; #define XB_SPIN(cond, bar) do { unsigned _sp = 0; while (cond) { __builtin_amdgcn_s_sleep(1); \
;     if ((++_sp & 255u) == 0u) { if (xb_ld(&(bar)[XB_TMO])) break; if (_sp > XB_SPIN_CAP) { atomicAdd(&(bar)[XB_TMO], 1u); break; } } } } while (0)
; __device__ __forceinline__ void xcd_barrier(const XcdBarrier& b) {
;     asm volatile("s_waitcnt vmcnt(0)" ::: "memory");
;     __syncthreads();
;     if (threadIdx.x == 0) {
;         unsigned* bar = b.bar;
;         __builtin_amdgcn_s_waitcnt(0);
;         unsigned nloc = b.st[0], nx = b.st[1];
;         if (nloc == 0u) { xcd_barrier_complete(bar, b.x, nloc, nx); b.st[0] = nloc; b.st[1] = nx; }
;         const unsigned old = xb_add(&bar[XB_XSUB(b.x)], 1u);
;         const unsigned gen = old / nloc;
;         if (old + 1u == (gen + 1u) * nloc) {
;             __builtin_amdgcn_fence(__ATOMIC_RELEASE, "agent");
;             asm volatile("s_waitcnt vmcnt(0)" ::: "memory");
;             const unsigned og = xb_add(&bar[XB_TOP], 1u);
;             const unsigned tg = og / nx;
;             if (og + 1u == (tg + 1u) * nx) xb_add(&bar[XB_TOPGEN], 1u);
;             else XB_SPIN(xb_ld(&bar[XB_TOPGEN]) == tg, bar);
;             __builtin_amdgcn_fence(__ATOMIC_ACQUIRE, "agent");
;             xb_add(&bar[XB_XGEN(b.x)], 1u);
;             asm volatile("s_waitcnt vmcnt(0)" ::: "memory");
;         } else {
;             XB_SPIN(xb_ld(&bar[XB_XGEN(b.x)]) == gen, bar);
;             __builtin_amdgcn_fence(__ATOMIC_ACQUIRE, "agent");
;             asm volatile("s_waitcnt vmcnt(0)" ::: "memory");
;         }
;     }
;     __syncthreads();
; }
.Lgd_nold:
	s_waitcnt vmcnt(0)
	s_barrier
	v_readlane_b32 s4, v1, 0
	s_nop 1
	v_cmp_ne_u32_e32 vcc, s4, v1
	s_and_b32 s5, vcc_lo, 0xf
	s_cmp_eq_u32 s5, 0
	s_cselect_b32 s5, 1, 0
	s_cmp_lg_u32 s4, 0
	s_cselect_b32 s98, s5, 0
	v_cmp_eq_u32_e32 vcc, 0, v0
	s_and_saveexec_b64 s[2:3], vcc
	s_cbranch_execz .LBB0_775
	s_cmp_eq_u32 s98, 1
	s_cbranch_scc1 .Lgd_noflush
	buffer_wbl2 sc1
	s_waitcnt vmcnt(0)
.Lgd_noflush:
	v_readlane_b32 s0, v255, 3
	s_lshr_b32 s1, s0, 5
	s_lshl_b32 s1, s1, 8
	s_add_i32 s1, s1, 0x54000
	s_lshr_b32 s0, s0, 2
	s_lshl_b32 s0, s0, 8
	s_add_i32 s0, s0, 0x55000
	v_mov_b32_e32 v2, 1
	v_mov_b32_e32 v1, s1
	global_atomic_add v1, v2, s[26:27]
	v_mov_b32_e32 v5, s0
	global_atomic_add v5, v2, s[26:27]
	s_mov_b32 exec_lo, 0x1ff
	s_mov_b32 exec_hi, 0
	s_mov_b32 s4, 0x54000
	v_lshl_add_u32 v1, v254, 8, s4
	v_mov_b32_e32 v4, 32
	v_mov_b32_e32 v5, s0
	v_cmp_eq_u32_e32 vcc, 8, v254
	s_nop 1
	v_cndmask_b32_e32 v1, v1, v5, vcc
	v_cndmask_b32_e64 v4, v4, 4, vcc
	s_mov_b32 s6, 0

; __device__ __forceinline__ unsigned xb_ld(unsigned* p)              { return __hip_atomic_load(p, __ATOMIC_RELAXED, __HIP_MEMORY_SCOPE_AGENT); }
; __device__ __forceinline__ unsigned xb_add(unsigned* p, unsigned v) { return __hip_atomic_fetch_add(p, v, __ATOMIC_RELAXED, __HIP_MEMORY_SCOPE_AGENT); }
; #define XB_SPIN(cond, bar) do { unsigned _sp = 0; while (cond) { __builtin_amdgcn_s_sleep(1); \
;     if ((++_sp & 255u) == 0u) { if (xb_ld(&(bar)[XB_TMO])) break; if (_sp > XB_SPIN_CAP) { atomicAdd(&(bar)[XB_TMO], 1u); break; } } } } while (0)
; __device__ __forceinline__ void xcd_barrier(const XcdBarrier& b) {
;     asm volatile("s_waitcnt vmcnt(0)" ::: "memory");
;     __syncthreads();
;     if (threadIdx.x == 0) {
;         unsigned* bar = b.bar;
;         __builtin_amdgcn_s_waitcnt(0);
;         unsigned nloc = b.st[0], nx = b.st[1];
;         if (nloc == 0u) { xcd_barrier_complete(bar, b.x, nloc, nx); b.st[0] = nloc; b.st[1] = nx; }
;         const unsigned old = xb_add(&bar[XB_XSUB(b.x)], 1u);
;         const unsigned gen = old / nloc;
;         if (old + 1u == (gen + 1u) * nloc) {
;             __builtin_amdgcn_fence(__ATOMIC_RELEASE, "agent");
;             asm volatile("s_waitcnt vmcnt(0)" ::: "memory");
;             const unsigned og = xb_add(&bar[XB_TOP], 1u);
;             const unsigned tg = og / nx;
;             if (og + 1u == (tg + 1u) * nx) xb_add(&bar[XB_TOPGEN], 1u);
;             else XB_SPIN(xb_ld(&bar[XB_TOPGEN]) == tg, bar);
;             __builtin_amdgcn_fence(__ATOMIC_ACQUIRE, "agent");
;             xb_add(&bar[XB_XGEN(b.x)], 1u);
;             asm volatile("s_waitcnt vmcnt(0)" ::: "memory");
;         } else {
;             XB_SPIN(xb_ld(&bar[XB_XGEN(b.x)]) == gen, bar);
;             __builtin_amdgcn_fence(__ATOMIC_ACQUIRE, "agent");
;             asm volatile("s_waitcnt vmcnt(0)" ::: "memory");
;         }
;     }
;     __syncthreads();
; }
.Lgc_nold:
	s_waitcnt vmcnt(0)
	s_barrier
	v_readlane_b32 s4, v1, 0
	s_nop 1
	v_cmp_ne_u32_e32 vcc, s4, v1
	s_and_b32 s5, vcc_lo, 0xff
	s_cmp_eq_u32 s5, 0
	s_cselect_b32 s5, 1, 0
	s_cmp_lg_u32 s4, 0
	s_cselect_b32 s98, s5, 0
	v_cmp_eq_u32_e32 vcc, 0, v0
	s_and_saveexec_b64 s[2:3], vcc
	s_cbranch_execz .LBB0_912
	s_cmp_eq_u32 s98, 1
	s_cbranch_scc1 .Lgc_noflush
	buffer_wbl2 sc1
	s_waitcnt vmcnt(0)

; __device__ __forceinline__ unsigned xb_ld(unsigned* p)              { return __hip_atomic_load(p, __ATOMIC_RELAXED, __HIP_MEMORY_SCOPE_AGENT); }
; __device__ __forceinline__ unsigned xb_add(unsigned* p, unsigned v) { return __hip_atomic_fetch_add(p, v, __ATOMIC_RELAXED, __HIP_MEMORY_SCOPE_AGENT); }
; #define XB_SPIN(cond, bar) do { unsigned _sp = 0; while (cond) { __builtin_amdgcn_s_sleep(1); \
;     if ((++_sp & 255u) == 0u) { if (xb_ld(&(bar)[XB_TMO])) break; if (_sp > XB_SPIN_CAP) { atomicAdd(&(bar)[XB_TMO], 1u); break; } } } } while (0)
; __device__ __forceinline__ void xcd_barrier(const XcdBarrier& b) {
;     asm volatile("s_waitcnt vmcnt(0)" ::: "memory");
;     __syncthreads();
;     if (threadIdx.x == 0) {
;         unsigned* bar = b.bar;
;         __builtin_amdgcn_s_waitcnt(0);
;         unsigned nloc = b.st[0], nx = b.st[1];
;         if (nloc == 0u) { xcd_barrier_complete(bar, b.x, nloc, nx); b.st[0] = nloc; b.st[1] = nx; }
;         const unsigned old = xb_add(&bar[XB_XSUB(b.x)], 1u);
;         const unsigned gen = old / nloc;
;         if (old + 1u == (gen + 1u) * nloc) {
;             __builtin_amdgcn_fence(__ATOMIC_RELEASE, "agent");
;             asm volatile("s_waitcnt vmcnt(0)" ::: "memory");
;             const unsigned og = xb_add(&bar[XB_TOP], 1u);
;             const unsigned tg = og / nx;
;             if (og + 1u == (tg + 1u) * nx) xb_add(&bar[XB_TOPGEN], 1u);
;             else XB_SPIN(xb_ld(&bar[XB_TOPGEN]) == tg, bar);
;             __builtin_amdgcn_fence(__ATOMIC_ACQUIRE, "agent");
;             xb_add(&bar[XB_XGEN(b.x)], 1u);
;             asm volatile("s_waitcnt vmcnt(0)" ::: "memory");
;         } else {
;             XB_SPIN(xb_ld(&bar[XB_XGEN(b.x)]) == gen, bar);
;             __builtin_amdgcn_fence(__ATOMIC_ACQUIRE, "agent");
;             asm volatile("s_waitcnt vmcnt(0)" ::: "memory");
;         }
;     }
;     __syncthreads();
; }
.LBB0_948:
	v_readlane_b32 s4, v255, 5
	v_readlane_b32 s5, v255, 6
	s_cmp_lt_i32 s5, 7
	s_cbranch_scc1 .LBB0_998
	v_readlane_b32 s0, v255, 9
	s_cmp_eq_u32 s0, 0
	s_cbranch_scc1 .Lgb_grid
	s_waitcnt vmcnt(0)
	s_barrier
	v_readlane_b32 s4, v1, 0
	s_nop 1
	v_cmp_ne_u32_e32 vcc, s4, v1
	s_and_b32 s5, vcc_lo, 0xff
	s_cmp_eq_u32 s5, 0
	s_cselect_b32 s5, 1, 0
	s_cmp_lg_u32 s4, 0
	s_cselect_b32 s98, s5, 0
	v_cmp_eq_u32_e32 vcc, 0, v0
	s_and_saveexec_b64 s[2:3], vcc
	s_cbranch_execz .LBB0_997
	s_cmp_eq_u32 s98, 1
	s_cbranch_scc1 .Lgb_noflush
	buffer_wbl2 sc1
	s_waitcnt vmcnt(0)
